# cache_conv items re-dealt to the 224 workgroups with 8 projin tiles and run 3 per tile inside the tile loop; K-path loads batched; attention coarser lgkm waits
# speedup vs baseline: 1.0617x; 1.0079x over previous
; #define VB() (2 * B + (TID512() >> 8))
; #define HS() (smem + (TID512() >> 8) * HALF_LDS)
; __global__ void __launch_bounds__(512, 2) mega(Params p) {
;     ...
;     if (ONLY < 0 || ONLY == 2) { int mt, nt; for (int k = 0; xcd_tile(B, G, k, 130, 16, mt, nt); ++k) projin_tile(p, l, mt, nt, smem); for (int it = VB(); it < PB_KC + PB_VC; it += vG) cache_conv_item(p, l, it, HS()); }
.LBB0_134:
	s_add_i32 s28, s28, 1
	s_mul_i32 s60, s28, 3
	s_add_i32 s60, s60, -3
	s_mov_b32 s61, 1
	s_branch .Lmy_cc_entry
.Lmy_cc_ret:
	v_readlane_b32 s6, v254, 39
	v_readlane_b32 s7, v254, 40
	s_lshl_b64 s[4:5], s[6:7], 20
	s_add_u32 s44, s92, s4
	s_addc_u32 s45, s93, s5
	v_readlane_b32 s4, v252, 41
	s_add_u32 s10, s4, s42
	v_readlane_b32 s4, v252, 42
	s_addc_u32 s11, s4, s43
	s_mov_b64 s[6:7], 0

; DI int TID() { int t = threadIdx.x & 255; asm volatile("" : "+v"(t)); return t; }
; DI unsigned pack2(float a, float b) { f32v2_t v = {a, b}; bf16v2_t r = __builtin_convertvector(v, bf16v2_t); return __builtin_bit_cast(unsigned, r); }
; #define VB() (2 * B + (TID512() >> 8))
; #define HS() (smem + (TID512() >> 8) * HALF_LDS)
; DI void cache_conv_item(const Params& p, int l, int it, char* smem) {
;   const int tid = TID();
;   if (it < PB_KC) {
;     const float* src = p.in[2] + (size_t)l * SBT * PAST * 512;
;     u16* KS = (u16*)(p.ws + O_KS);
; #pragma unroll
;     for (int i = 0; i < 4; ++i) {
;       size_t e = (size_t)it * 4096 + (size_t)(tid + i * 256) * 4;
;       const f32x4 vv = __builtin_nontemporal_load((const f32x4*)(src + e));
;       const float4 v = {vv[0], vv[1], vv[2], vv[3]};
;       size_t b = e / ((size_t)PAST * 512), r = e % ((size_t)PAST * 512);
;       *(uint2*)(KS + b * SKP * 512 + r) = uint2{pack2(v.x, v.y), pack2(v.z, v.w)};
;     }
;     return;
;   }
;   it -= PB_KC;
;   const int b = it / 256, r = it % 256, ptile = r / 8, ctile = r % 8;
;   const float* src = p.in[3] + ((size_t)l * SBT + b) * PAST * 512;
;   u16* VTS = (u16*)(p.ws + O_VTS);
;   transpose_tile(src, 512, ptile * 64, ctile * 64, 64, VTS + (size_t)b * 512 * SKP, SKP, ctile * 64, (float*)smem);
; __global__ void __launch_bounds__(512, 2) mega(Params p) {
;     ...
;     if (ONLY < 0 || ONLY == 2) { int mt, nt; for (int k = 0; xcd_tile(B, G, k, 130, 16, mt, nt); ++k) projin_tile(p, l, mt, nt, smem); for (int it = VB(); it < PB_KC + PB_VC; it += vG) cache_conv_item(p, l, it, HS()); }
.LBB0_1252:
	s_mul_i32 s60, s28, 3
	s_mov_b32 s61, 0
.Lmy_cc_entry:
	v_readlane_b32 s4, v251, 5
	s_lshr_b32 s5, s4, 4
	s_bfe_u32 s6, s4, 0x30001
	s_min_u32 s7, s5, 16
	s_lshl_b32 s7, s7, 1
	s_min_u32 s8, s6, 2
	s_cmp_lt_u32 s5, 16
	s_cselect_b32 s8, s8, 0
	s_cselect_b32 s9, 1, 0
	s_add_i32 s7, s7, s8
	s_cmp_lt_u32 s6, 2
	s_cselect_b32 s8, s9, 0
	s_lshl_b32 s7, s7, 1
	s_sub_i32 s4, s4, s7
	s_mul_i32 s5, s60, 0x1c0
	s_add_i32 s62, s4, s5
	s_add_i32 s63, s62, 0x540
	s_cmp_eq_u32 s61, 0
	s_cselect_b32 s63, 0x2000, s63
	s_min_i32 s63, s63, 0x2000
	s_cmp_lg_u32 s8, 0
	s_cselect_b32 s63, 0, s63
	v_mov_b32_e32 v0, v184
	v_ashrrev_i32_e32 v0, 8, v0
	v_add_u32_e32 v2, s62, v0
	v_cmp_gt_i32_e32 vcc, s63, v2
	s_and_saveexec_b64 s[4:5], vcc
	s_cbranch_execz .LBB0_1259
	v_readlane_b32 s44, v254, 41
	v_readlane_b32 s45, v254, 42
	v_readlane_b32 s46, v254, 43
	v_readlane_b32 s47, v254, 44
	v_lshlrev_b32_e32 v10, 3, v2
	v_lshlrev_b32_e32 v11, 6, v2
	v_mov_b32_e32 v4, v2
	v_mov_b32_e32 v5, 0
	s_add_u32 s6, s46, s42
	s_addc_u32 s7, s47, s43
	v_lshlrev_b64 v[0:1], 14, v[4:5]
	v_lshl_add_u64 v[0:1], s[44:45], 0, v[0:1]
	v_lshlrev_b64 v[4:5], 12, v[4:5]
	s_mov_b64 s[8:9], 0
	v_readlane_b32 s48, v254, 45
	v_readlane_b32 s49, v254, 46
	v_readlane_b32 s50, v254, 47
	v_readlane_b32 s51, v254, 48
	v_readlane_b32 s52, v254, 49
	v_readlane_b32 s53, v254, 50
	v_readlane_b32 s54, v254, 51
	v_readlane_b32 s55, v254, 52
	v_readlane_b32 s56, v254, 53
	v_readlane_b32 s57, v254, 54
	v_readlane_b32 s58, v254, 55
	v_readlane_b32 s59, v254, 56
	s_branch .LBB0_1255
.LBB0_1254:
	s_or_b64 exec, exec, s[12:13]
	v_add_u32_e32 v2, 0x1c0, v2
	v_add_u32_e32 v10, 0xe00, v10
	v_add_u32_e32 v11, 0x7000, v11
	s_mov_b64 s[10:11], 0x700000
	v_lshl_add_u64 v[0:1], v[0:1], 0, s[10:11]
	v_cmp_le_i32_e32 vcc, s63, v2
	s_mov_b64 s[10:11], 0x1c0000
	s_or_b64 s[8:9], vcc, s[8:9]
	v_lshl_add_u64 v[4:5], v[4:5], 0, s[10:11]
	s_andn2_b64 exec, exec, s[8:9]
	s_cbranch_execz .LBB0_1259

; DI unsigned pack2(float a, float b) { f32v2_t v = {a, b}; bf16v2_t r = __builtin_convertvector(v, bf16v2_t); return __builtin_bit_cast(unsigned, r); }
; DI void cache_conv_item(const Params& p, int l, int it, char* smem) {
;     ...
;   if (it < PB_KC) {
;     const float* src = p.in[2] + (size_t)l * SBT * PAST * 512;
;     u16* KS = (u16*)(p.ws + O_KS);
; #pragma unroll
;     for (int i = 0; i < 4; ++i) {
;       size_t e = (size_t)it * 4096 + (size_t)(tid + i * 256) * 4;
;       const f32x4 vv = __builtin_nontemporal_load((const f32x4*)(src + e));
;       const float4 v = {vv[0], vv[1], vv[2], vv[3]};
;       size_t b = e / ((size_t)PAST * 512), r = e % ((size_t)PAST * 512);
;       *(uint2*)(KS + b * SKP * 512 + r) = uint2{pack2(v.x, v.y), pack2(v.z, v.w)};
;     }
;     return;
; __device__ __forceinline__ void xcd_barrier(const XcdBarrier& b) {
;     asm volatile("s_waitcnt vmcnt(0)" ::: "memory");
;     __syncthreads();
;     if (threadIdx.x == 0) {
;         unsigned* bar = b.bar;
;         __builtin_amdgcn_s_waitcnt(0);
;         unsigned nloc = b.st[0], nx = b.st[1];
;         if (nloc == 0u) { xcd_barrier_complete(bar, b.x, nloc, nx); b.st[0] = nloc; b.st[1] = nx; }
.LBB0_1257:
	s_andn2_saveexec_b64 s[12:13], s[12:13]
	s_cbranch_execz .LBB0_1254
	v_ashrrev_i32_e32 v9, 31, v8
	s_mov_b64 s[24:25], 0x1000
	v_lshl_add_u64 v[6:7], v[8:9], 4, v[0:1]
	v_lshl_add_u64 v[16:17], v[8:9], 2, v[4:5]
	global_load_dwordx4 v[12:15], v[6:7], off nt
	v_lshl_add_u64 v[6:7], v[6:7], 0, s[24:25]
	global_load_dwordx4 v[20:23], v[6:7], off nt
	v_lshl_add_u64 v[6:7], v[6:7], 0, s[24:25]
	global_load_dwordx4 v[24:27], v[6:7], off nt
	v_lshl_add_u64 v[6:7], v[6:7], 0, s[24:25]
	global_load_dwordx4 v[28:31], v[6:7], off nt
	v_readlane_b32 s10, v252, 39
	v_readlane_b32 s11, v252, 40
	s_mov_b32 s20, 0x210000
	v_and_b32_e32 v9, 0xffffc, v16
	v_mov_b64_e32 v[6:7], s[10:11]
	v_lshlrev_b32_e32 v172, 1, v9
	v_alignbit_b32 v18, v17, v16, 20
	v_mad_u64_u32 v[18:19], s[10:11], v18, s20, v[6:7]
	v_lshrrev_b32_e32 v16, 20, v17
	v_mad_u32_u24 v19, v16, s20, v19
	v_lshl_add_u64 v[18:19], v[18:19], 0, v[172:173]
	v_lshl_add_u64 v[16:17], v[18:19], 0, s[24:25]
	s_waitcnt vmcnt(3)
	v_cvt_pk_bf16_f32 v12, v12, v13
	v_cvt_pk_bf16_f32 v13, v14, v15
	global_store_dwordx2 v[18:19], v[12:13], off
	s_waitcnt vmcnt(3)
	v_cvt_pk_bf16_f32 v20, v20, v21
	v_cvt_pk_bf16_f32 v21, v22, v23
	global_store_dwordx2 v[18:19], v[20:21], off offset:2048
	s_waitcnt vmcnt(3)
	v_cvt_pk_bf16_f32 v24, v24, v25
	v_cvt_pk_bf16_f32 v25, v26, v27
	global_store_dwordx2 v[16:17], v[24:25], off
	s_waitcnt vmcnt(3)
	v_cvt_pk_bf16_f32 v28, v28, v29
	v_cvt_pk_bf16_f32 v29, v30, v31
	global_store_dwordx2 v[16:17], v[28:29], off offset:2048
	s_branch .LBB0_1254
.LBB0_1259:
	s_or_b64 exec, exec, s[4:5]
	s_cmp_lg_u32 s61, 0
	s_cbranch_scc1 .Lmy_cc_ret
	s_waitcnt vmcnt(0)
	s_waitcnt vmcnt(0)
	s_barrier
	s_mov_b64 s[4:5], exec
	v_readlane_b32 s6, v251, 3
	v_readlane_b32 s7, v251, 4
	s_and_b64 s[6:7], s[4:5], s[6:7]
	s_mov_b64 exec, s[6:7]
	s_cbranch_execz .LBB0_1311
	s_waitcnt vmcnt(0) expcnt(0) lgkmcnt(0)
	ds_read_b32 v2, v173
	ds_read_b32 v0, v173 offset:4
	s_waitcnt lgkmcnt(1)
	v_cmp_ne_u32_e32 vcc, 0, v2
	s_cbranch_vccnz .LBB0_1275
	s_mov_b32 s10, 1
	s_branch .LBB0_1263

; #define MFMA16(a, b, c) __builtin_amdgcn_mfma_f32_16x16x32_bf16((a), (b), (c), 0, 0, 0)
; DI int kswz(int key) { return (((key >> 3) & 3) << 2) | (key & 3); }
; DI void attn_item(const Params& p, int l, bool isS, int b, int h, int cp, char* smem) {
;     ...
;   auto qk_tile = [&](int kt, f32x4 (&st)[2][4]) {
;     const char* Kb = Ks + (kt & 1) * 16384;
;     bf16x8 kf[2][4][2];
; #pragma unroll
;     for (int mp = 0; mp < 2; ++mp)
; #pragma unroll
;       for (int mt = 0; mt < 4; ++mt) {
;         const int key = 32 * (mt >> 1) + 8 * (fr >> 2) + 4 * (mt & 1) + (fr & 3);
; #pragma unroll
;         for (int ks = 0; ks < 2; ++ks) kf[mp][mt][ks] = *(const bf16x8*)(Kb + key * 256 + (((mp * 8 + ks * 4 + fq) ^ kswz(key)) << 4));
;       }
; #pragma unroll
;     for (int mp = 0; mp < 2; ++mp)
; #pragma unroll
;       for (int mt = 0; mt < 4; ++mt) {
;         f32x4 a = MFMA16(kf[mp][mt][0], qf[mp][0], (f32x4{0.f, 0.f, 0.f, 0.f}));
;         st[mp][mt] = MFMA16(kf[mp][mt][1], qf[mp][1], a);
;       }
;     if ((kt + 1) * 64 > klen) {
;       asm volatile("" ::: "memory");
; #pragma unroll
;       for (int mp = 0; mp < 2; ++mp)
; #pragma unroll
;         for (int mt = 0; mt < 4; ++mt)
; #pragma unroll
;           for (int j = 0; j < 4; ++j) {
;             const int key = kt * 64 + 32 * (mt >> 1) + 8 * fq + 4 * (mt & 1) + j;
;             if (key >= klen) st[mp][mt][j] = -INFINITY;
;           }
;     }
;     ...
;       const char* Vb = Vs + (j & 1) * 16384;
; #pragma unroll
;       for (int nh = 0; nh < 2; ++nh) {
;         bf16x8 vf[4][2];
; #pragma unroll
;         for (int n = 0; n < 4; ++n) {
;           const int vd = (nh * 4 + n) * 16 + fr;
; #pragma unroll
;           for (int s = 0; s < 2; ++s) vf[n][s] = *(const bf16x8*)(Vb + vd * 128 + (((s * 4 + fq) ^ ((vd >> 1) & 7)) << 4));
;         }
.LBB0_1376:
	s_andn2_saveexec_b64 s[28:29], s[28:29]
	s_cbranch_execz .LBB0_1386
	s_add_i32 s20, s34, 0x4000
	s_and_b32 s20, s20, 0x4000
	v_add_u32_e32 v248, s20, v151
	v_add_u32_e32 v170, v248, v146
	v_add_u32_e32 v171, v248, v147
	v_add_u32_e32 v242, v248, v148
	v_add_u32_e32 v243, v248, v149
	s_and_b32 s24, s34, 0x4000
	v_add_u32_e32 v249, s24, v150
	v_add_u32_e32 v244, v249, v137
	v_add_u32_e32 v245, v249, v145
	ds_read_b128 v[154:157], v170
	ds_read_b128 v[158:161], v171
	ds_read_b128 v[162:165], v170 offset:1024
	ds_read_b128 v[166:169], v171 offset:1024
	ds_read_b128 v[176:179], v170 offset:8192
	ds_read_b128 v[180:183], v171 offset:8192
	ds_read_b128 v[198:201], v170 offset:9216
	ds_read_b128 v[202:205], v171 offset:9216
	ds_read_b128 v[206:209], v242
	ds_read_b128 v[214:217], v243
	ds_read_b128 v[218:221], v242 offset:1024
	ds_read_b128 v[222:225], v243 offset:1024
	ds_read_b128 v[226:229], v242 offset:8192
	ds_read_b128 v[230:233], v243 offset:8192
	ds_read_b128 v[234:237], v242 offset:9216
	s_waitcnt lgkmcnt(13)
	v_mfma_f32_16x16x32_bf16 v[124:127], v[154:157], v[8:11], 0
	v_mfma_f32_16x16x32_bf16 v[124:127], v[158:161], v[4:7], v[124:127]
	ds_read_b128 v[238:241], v243 offset:9216
	s_waitcnt lgkmcnt(12)
	v_mfma_f32_16x16x32_bf16 v[120:123], v[162:165], v[8:11], 0
	v_mfma_f32_16x16x32_bf16 v[120:123], v[166:169], v[4:7], v[120:123]
	s_waitcnt lgkmcnt(10)
	v_mfma_f32_16x16x32_bf16 v[112:115], v[176:179], v[8:11], 0
	v_mfma_f32_16x16x32_bf16 v[112:115], v[180:183], v[4:7], v[112:115]
	s_waitcnt lgkmcnt(8)
	v_mfma_f32_16x16x32_bf16 v[116:119], v[198:201], v[8:11], 0
	v_mfma_f32_16x16x32_bf16 v[116:119], v[202:205], v[4:7], v[116:119]
	ds_read_b128 v[154:157], v244 offset:32768
	ds_read_b128 v[158:161], v245 offset:32768
	ds_read_b128 v[162:165], v244 offset:34816
	ds_read_b128 v[166:169], v245 offset:34816
	ds_read_b128 v[176:179], v244 offset:36864
	ds_read_b128 v[180:183], v245 offset:36864
	ds_read_b128 v[198:201], v244 offset:38912
	s_waitcnt lgkmcnt(13)
	v_mfma_f32_16x16x32_bf16 v[104:107], v[206:209], v[16:19], 0
	v_mfma_f32_16x16x32_bf16 v[104:107], v[214:217], v[12:15], v[104:107]
	ds_read_b128 v[202:205], v245 offset:38912
	s_waitcnt lgkmcnt(12)
	v_mfma_f32_16x16x32_bf16 v[108:111], v[218:221], v[16:19], 0
	v_mfma_f32_16x16x32_bf16 v[108:111], v[222:225], v[12:15], v[108:111]
	s_waitcnt lgkmcnt(10)
	v_mfma_f32_16x16x32_bf16 v[100:103], v[226:229], v[16:19], 0
	v_mfma_f32_16x16x32_bf16 v[100:103], v[230:233], v[12:15], v[100:103]
	s_waitcnt lgkmcnt(8)
	v_mfma_f32_16x16x32_bf16 v[128:131], v[234:237], v[16:19], 0
	v_mfma_f32_16x16x32_bf16 v[128:131], v[238:241], v[12:15], v[128:131]
	ds_read_b128 v[206:209], v244 offset:40960
	ds_read_b128 v[214:217], v245 offset:40960
	ds_read_b128 v[218:221], v244 offset:43008
	ds_read_b128 v[222:225], v245 offset:43008
	ds_read_b128 v[226:229], v244 offset:45056
	ds_read_b128 v[230:233], v245 offset:45056
	ds_read_b128 v[234:237], v244 offset:47104
	s_add_i32 s20, s11, 0x80
	s_cmp_le_i32 s20, s10
	s_cbranch_scc1 .Lat_nomask
	s_nop 7
	v_add_u32_e32 v246, s11, v132
	v_add_u32_e32 v247, 64, v246
	v_cmp_gt_i32_e64 s[38:39], s10, v247
	v_add_u32_e32 v247, 0x41, v246
	v_cmp_gt_i32_e64 s[40:41], s10, v247
	v_add_u32_e32 v247, 0x42, v246
	v_cmp_gt_i32_e64 s[42:43], s10, v247
	v_add_u32_e32 v247, 0x43, v246
	v_cmp_gt_i32_e64 s[44:45], s10, v247
	v_add_u32_e32 v247, 0x44, v246
	v_cmp_gt_i32_e64 s[46:47], s10, v247
	v_add_u32_e32 v247, 0x45, v246
	v_cmp_gt_i32_e64 s[48:49], s10, v247
	v_add_u32_e32 v247, 0x46, v246
	v_cmp_gt_i32_e64 s[50:51], s10, v247
	v_add_u32_e32 v247, 0x47, v246
	v_cmp_gt_i32_e64 s[52:53], s10, v247
	v_add_u32_e32 v247, 0x60, v246
	v_cmp_gt_i32_e64 s[54:55], s10, v247
	v_add_u32_e32 v247, 0x61, v246
	v_cmp_gt_i32_e64 s[56:57], s10, v247
	v_add_u32_e32 v247, 0x62, v246
	v_cmp_gt_i32_e64 s[58:59], s10, v247
	v_add_u32_e32 v247, 0x63, v246
	v_cmp_gt_i32_e64 s[60:61], s10, v247
	v_add_u32_e32 v247, 0x64, v246
	v_cmp_gt_i32_e64 s[62:63], s10, v247
	v_add_u32_e32 v247, 0x65, v246
	v_cmp_gt_i32_e64 s[64:65], s10, v247
	v_add_u32_e32 v247, 0x66, v246
	v_add_u32_e32 v246, 0x67, v246
	v_cmp_gt_i32_e64 s[66:67], s10, v246
	v_cmp_gt_i32_e64 s[68:69], s10, v247
	v_cmp_le_i32_e32 vcc, s10, v246
	v_cndmask_b32_e64 v119, v3, v119, s[66:67]
	s_or_b64 s[66:67], s[66:67], s[68:69]
	v_cndmask_b32_e64 v118, v3, v118, s[66:67]
	s_or_b64 s[66:67], s[66:67], s[64:65]
	s_or_b64 s[64:65], s[68:69], s[64:65]
	v_cndmask_b32_e64 v117, v3, v117, s[66:67]
	s_or_b64 s[66:67], s[66:67], s[62:63]
	s_or_b64 s[62:63], s[64:65], s[62:63]
	v_cndmask_b32_e64 v116, v3, v116, s[66:67]
	s_or_b64 s[66:67], s[66:67], s[60:61]
	s_or_b64 s[60:61], s[62:63], s[60:61]
	v_cndmask_b32_e64 v115, v3, v115, s[66:67]
	s_or_b64 s[66:67], s[66:67], s[58:59]
	s_or_b64 s[58:59], s[60:61], s[58:59]
	v_cndmask_b32_e64 v114, v3, v114, s[66:67]
	s_or_b64 s[66:67], s[66:67], s[56:57]
	s_or_b64 s[56:57], s[58:59], s[56:57]
	v_cndmask_b32_e64 v113, v3, v113, s[66:67]
	s_or_b64 s[66:67], s[66:67], s[54:55]
	s_or_b64 s[54:55], s[56:57], s[54:55]
	v_cndmask_b32_e64 v112, v3, v112, s[66:67]
	s_or_b64 s[66:67], s[66:67], s[52:53]
	s_or_b64 s[52:53], s[54:55], s[52:53]
	v_cndmask_b32_e64 v123, v3, v123, s[66:67]
	s_or_b64 s[66:67], s[66:67], s[50:51]
	s_or_b64 s[50:51], s[52:53], s[50:51]
	v_cndmask_b32_e64 v122, v3, v122, s[66:67]
	s_or_b64 s[66:67], s[66:67], s[48:49]
	s_or_b64 s[48:49], s[50:51], s[48:49]
	v_cndmask_b32_e64 v121, v3, v121, s[66:67]
	s_or_b64 s[66:67], s[66:67], s[46:47]
	s_or_b64 s[46:47], s[48:49], s[46:47]
	v_cndmask_b32_e64 v120, v3, v120, s[66:67]
	s_or_b64 s[66:67], s[66:67], s[44:45]
	s_or_b64 s[44:45], s[46:47], s[44:45]
	v_cndmask_b32_e64 v127, v3, v127, s[66:67]
	s_or_b64 s[66:67], s[66:67], s[42:43]
	s_or_b64 s[42:43], s[44:45], s[42:43]
	v_cndmask_b32_e64 v126, v3, v126, s[66:67]
	s_or_b64 s[66:67], s[66:67], s[40:41]
	s_or_b64 s[40:41], s[42:43], s[40:41]
	v_cndmask_b32_e64 v125, v3, v125, s[66:67]
	s_or_b64 s[66:67], s[66:67], s[38:39]
	s_or_b64 s[38:39], s[40:41], s[38:39]
	v_cndmask_b32_e64 v130, v3, v130, s[68:69]
	v_cndmask_b32_e64 v124, v3, v124, s[66:67]
	v_cndmask_b32_e64 v129, v3, v129, s[64:65]
	v_cndmask_b32_e64 v128, v3, v128, s[62:63]
	v_cndmask_b32_e64 v103, v3, v103, s[60:61]
	v_cndmask_b32_e64 v102, v3, v102, s[58:59]
	v_cndmask_b32_e64 v101, v3, v101, s[56:57]
	v_cndmask_b32_e64 v100, v3, v100, s[54:55]
	v_cndmask_b32_e64 v111, v3, v111, s[52:53]
	v_cndmask_b32_e64 v110, v3, v110, s[50:51]
	v_cndmask_b32_e64 v109, v3, v109, s[48:49]
	v_cndmask_b32_e64 v108, v3, v108, s[46:47]
	v_cndmask_b32_e64 v107, v3, v107, s[44:45]
	v_cndmask_b32_e64 v106, v3, v106, s[42:43]
	v_cndmask_b32_e64 v105, v3, v105, s[40:41]
	v_cndmask_b32_e64 v104, v3, v104, s[38:39]
	s_and_saveexec_b64 s[30:31], vcc
	v_mov_b32_e32 v131, 0xff800000
	s_or_b64 exec, exec, s[30:31]
; #define MFMA16(a, b, c) __builtin_amdgcn_mfma_f32_16x16x32_bf16((a), (b), (c), 0, 0, 0)
; DI unsigned pack2(float a, float b) { f32v2_t v = {a, b}; bf16v2_t r = __builtin_convertvector(v, bf16v2_t); return __builtin_bit_cast(unsigned, r); }
; DI void attn_item(const Params& p, int l, bool isS, int b, int h, int cp, char* smem) {
;     ...
;   auto softmax_tile = [&](f32x4 (&st)[2][4], bf16x8 (&pfn)[2][2], float (&alpha)[2], float (&psum)[2], bool (&moved)[2]) {
; #pragma unroll
;     for (int mp = 0; mp < 2; ++mp) {
;       float mx = -INFINITY;
; #pragma unroll
;       for (int mt = 0; mt < 4; ++mt)
; #pragma unroll
;         for (int j = 0; j < 4; ++j) mx = fmaxf(mx, st[mp][mt][j]);
;       mx = quad_max(mx);
;       const float mold = mrun[mp];
;       const float mnew = fmaxf(mold, mx);
;       mrun[mp] = mnew;
;       float ps = 0.f;
; #pragma unroll
;       for (int mt = 0; mt < 4; ++mt)
; #pragma unroll
;         for (int j = 0; j < 4; ++j) { float e = __builtin_amdgcn_exp2f(st[mp][mt][j] - mnew); st[mp][mt][j] = e; ps += e; }
;       psum[mp] = ps;
;       moved[mp] = __any(mnew > mold);
;       alpha[mp] = __builtin_amdgcn_exp2f(mold - mnew);
; #pragma unroll
;       for (int s = 0; s < 2; ++s) {
;         uint4 u = {pack2(st[mp][2 * s][0], st[mp][2 * s][1]), pack2(st[mp][2 * s][2], st[mp][2 * s][3]),
;                    pack2(st[mp][2 * s + 1][0], st[mp][2 * s + 1][1]), pack2(st[mp][2 * s + 1][2], st[mp][2 * s + 1][3])};
;         pfn[mp][s] = __builtin_bit_cast(bf16x8, u);
;       }
;     }
;   };
;     ...
;     auto pv_tile = [&]() {
;       const char* Vb = Vs + (j & 1) * 16384;
; #pragma unroll
;       for (int nh = 0; nh < 2; ++nh) {
;         bf16x8 vf[4][2];
; #pragma unroll
;         for (int n = 0; n < 4; ++n) {
;           const int vd = (nh * 4 + n) * 16 + fr;
; #pragma unroll
;           for (int s = 0; s < 2; ++s) vf[n][s] = *(const bf16x8*)(Vb + vd * 128 + (((s * 4 + fq) ^ ((vd >> 1) & 7)) << 4));
;         }
; #pragma unroll
;         for (int n = 0; n < 4; ++n)
; #pragma unroll
;           for (int s = 0; s < 2; ++s) {
;             ot[0][nh * 4 + n] = MFMA16(vf[n][s], pf[0][s], ot[0][nh * 4 + n]);
;             ot[1][nh * 4 + n] = MFMA16(vf[n][s], pf[1][s], ot[1][nh * 4 + n]);
;           }
;       }
.Lat_nomask:
	s_mov_b32 s20, 0xff800000
	s_waitcnt lgkmcnt(14)
	v_mfma_f32_16x16x32_bf16 v[72:75], v[154:157], v[84:87], v[72:75]
	ds_read_b128 v[238:241], v245 offset:47104
	v_max3_f32 v246, v124, s20, v125
	v_max3_f32 v246, v246, v126, v127
	v_max3_f32 v246, v246, v120, v121
	v_max3_f32 v246, v246, v122, v123
	s_waitcnt lgkmcnt(14)
	v_mfma_f32_16x16x32_bf16 v[68:71], v[154:157], v[92:95], v[68:71]
	v_max3_f32 v246, v246, v112, v113
	v_max3_f32 v246, v246, v114, v115
	v_max3_f32 v246, v246, v116, v117
	v_max3_f32 v246, v246, v118, v119
	v_mfma_f32_16x16x32_bf16 v[72:75], v[158:161], v[88:91], v[72:75]
	v_mov_b32_e32 v248, v246
	s_nop 1
	v_permlane16_swap_b32_e32 v246, v248
	v_max_f32_e32 v246, v246, v248
	v_mov_b32_e32 v248, v246
	v_mfma_f32_16x16x32_bf16 v[68:71], v[158:161], v[96:99], v[68:71]
	s_nop 0
	v_permlane32_swap_b32_e32 v246, v248
	v_max3_f32 v246, v153, v246, v248
	v_cmp_gt_f32_e64 s[36:37], v246, v153
	v_max3_f32 v247, v104, s20, v105
	s_waitcnt lgkmcnt(12)
	v_mfma_f32_16x16x32_bf16 v[60:63], v[162:165], v[84:87], v[60:63]
	v_max3_f32 v247, v247, v106, v107
	v_max3_f32 v247, v247, v108, v109
	v_max3_f32 v247, v247, v110, v111
	v_max3_f32 v247, v247, v100, v101
	v_mfma_f32_16x16x32_bf16 v[64:67], v[162:165], v[92:95], v[64:67]
	v_max3_f32 v247, v247, v102, v103
	v_max3_f32 v247, v247, v128, v129
	v_max3_f32 v247, v247, v130, v131
	v_mov_b32_e32 v248, v247
	v_mfma_f32_16x16x32_bf16 v[60:63], v[166:169], v[88:91], v[60:63]
	s_nop 0
	v_permlane16_swap_b32_e32 v247, v248
	v_max_f32_e32 v247, v247, v248
	v_mov_b32_e32 v248, v247
	s_nop 1
	v_permlane32_swap_b32_e32 v247, v248
	v_mfma_f32_16x16x32_bf16 v[64:67], v[166:169], v[96:99], v[64:67]
	v_max3_f32 v247, v152, v247, v248
	v_cmp_gt_f32_e64 s[40:41], v247, v152
	v_sub_f32_e32 v124, v124, v246
	v_exp_f32_e32 v124, v124
	s_waitcnt lgkmcnt(10)
	v_mfma_f32_16x16x32_bf16 v[52:55], v[176:179], v[84:87], v[52:55]
	v_sub_f32_e32 v125, v125, v246
	v_exp_f32_e32 v125, v125
	v_sub_f32_e32 v126, v126, v246
	v_exp_f32_e32 v126, v126
	v_mfma_f32_16x16x32_bf16 v[56:59], v[176:179], v[92:95], v[56:59]
	v_add_f32_e32 v249, v124, v125
	v_sub_f32_e32 v127, v127, v246
	v_exp_f32_e32 v127, v127
	v_add_f32_e32 v249, v126, v249
	v_mfma_f32_16x16x32_bf16 v[52:55], v[180:183], v[88:91], v[52:55]
	v_sub_f32_e32 v120, v120, v246
	v_exp_f32_e32 v120, v120
	v_add_f32_e32 v249, v127, v249
	v_sub_f32_e32 v121, v121, v246
	v_mfma_f32_16x16x32_bf16 v[56:59], v[180:183], v[96:99], v[56:59]
	v_exp_f32_e32 v121, v121
	v_add_f32_e32 v249, v120, v249
	v_sub_f32_e32 v122, v122, v246
	v_exp_f32_e32 v122, v122
	s_waitcnt lgkmcnt(8)
	v_mfma_f32_16x16x32_bf16 v[48:51], v[198:201], v[84:87], v[48:51]
	v_add_f32_e32 v249, v121, v249
	v_sub_f32_e32 v123, v123, v246
	v_exp_f32_e32 v123, v123
	v_add_f32_e32 v249, v122, v249
	v_mfma_f32_16x16x32_bf16 v[24:27], v[198:201], v[92:95], v[24:27]
	v_sub_f32_e32 v112, v112, v246
	v_exp_f32_e32 v112, v112
	v_add_f32_e32 v249, v123, v249
	v_sub_f32_e32 v113, v113, v246
	v_mfma_f32_16x16x32_bf16 v[48:51], v[202:205], v[88:91], v[48:51]
	v_exp_f32_e32 v113, v113
	v_add_f32_e32 v249, v112, v249
	v_sub_f32_e32 v114, v114, v246
	v_exp_f32_e32 v114, v114
	v_mfma_f32_16x16x32_bf16 v[24:27], v[202:205], v[96:99], v[24:27]
	v_add_f32_e32 v249, v113, v249
	v_sub_f32_e32 v115, v115, v246
	v_exp_f32_e32 v115, v115
	v_add_f32_e32 v249, v114, v249
	s_waitcnt lgkmcnt(6)
	v_mfma_f32_16x16x32_bf16 v[40:43], v[206:209], v[84:87], v[40:43]
	v_sub_f32_e32 v116, v116, v246
	v_exp_f32_e32 v116, v116
	v_add_f32_e32 v249, v115, v249
	v_sub_f32_e32 v117, v117, v246
	v_mfma_f32_16x16x32_bf16 v[44:47], v[206:209], v[92:95], v[44:47]
	v_exp_f32_e32 v117, v117
	v_add_f32_e32 v249, v116, v249
	v_sub_f32_e32 v118, v118, v246
	v_exp_f32_e32 v118, v118
	v_mfma_f32_16x16x32_bf16 v[40:43], v[214:217], v[88:91], v[40:43]
	v_add_f32_e32 v249, v117, v249
	v_sub_f32_e32 v119, v119, v246
	v_exp_f32_e32 v119, v119
	v_add_f32_e32 v249, v118, v249
	v_mfma_f32_16x16x32_bf16 v[44:47], v[214:217], v[96:99], v[44:47]
	v_add_f32_e32 v249, v119, v249
	v_sub_f32_e32 v104, v104, v247
	v_exp_f32_e32 v104, v104
	v_sub_f32_e32 v105, v105, v247
	s_waitcnt lgkmcnt(4)
	v_mfma_f32_16x16x32_bf16 v[36:39], v[218:221], v[84:87], v[36:39]
	v_exp_f32_e32 v105, v105
	v_sub_f32_e32 v106, v106, v247
	v_exp_f32_e32 v106, v106
	v_add_f32_e32 v248, v104, v105
	v_mfma_f32_16x16x32_bf16 v[32:35], v[218:221], v[92:95], v[32:35]
	v_sub_f32_e32 v107, v107, v247
	v_exp_f32_e32 v107, v107
	v_add_f32_e32 v248, v106, v248
	v_sub_f32_e32 v108, v108, v247
	v_mfma_f32_16x16x32_bf16 v[36:39], v[222:225], v[88:91], v[36:39]
	v_exp_f32_e32 v108, v108
	v_add_f32_e32 v248, v107, v248
	v_sub_f32_e32 v109, v109, v247
	v_exp_f32_e32 v109, v109
	v_mfma_f32_16x16x32_bf16 v[32:35], v[222:225], v[96:99], v[32:35]
	v_add_f32_e32 v248, v108, v248
	v_sub_f32_e32 v110, v110, v247
	v_exp_f32_e32 v110, v110
	v_add_f32_e32 v248, v109, v248
	s_waitcnt lgkmcnt(2)
	v_mfma_f32_16x16x32_bf16 v[20:23], v[226:229], v[84:87], v[20:23]
	v_sub_f32_e32 v111, v111, v247
	v_exp_f32_e32 v111, v111
	v_add_f32_e32 v248, v110, v248
	v_sub_f32_e32 v100, v100, v247
	v_mfma_f32_16x16x32_bf16 v[28:31], v[226:229], v[92:95], v[28:31]
	v_exp_f32_e32 v100, v100
	v_add_f32_e32 v248, v111, v248
	v_sub_f32_e32 v101, v101, v247
	v_exp_f32_e32 v101, v101
	v_mfma_f32_16x16x32_bf16 v[20:23], v[230:233], v[88:91], v[20:23]
	v_add_f32_e32 v248, v100, v248
	v_sub_f32_e32 v102, v102, v247
	v_exp_f32_e32 v102, v102
	v_add_f32_e32 v248, v101, v248
	v_mfma_f32_16x16x32_bf16 v[28:31], v[230:233], v[96:99], v[28:31]
	v_sub_f32_e32 v103, v103, v247
	v_exp_f32_e32 v103, v103
	v_add_f32_e32 v248, v102, v248
	v_sub_f32_e32 v128, v128, v247
	s_waitcnt lgkmcnt(0)
	v_mfma_f32_16x16x32_bf16 v[76:79], v[234:237], v[84:87], v[76:79]
	v_exp_f32_e32 v128, v128
	v_add_f32_e32 v248, v103, v248
	v_sub_f32_e32 v129, v129, v247
	v_exp_f32_e32 v129, v129
	v_mfma_f32_16x16x32_bf16 v[80:83], v[234:237], v[92:95], v[80:83]
	v_add_f32_e32 v248, v128, v248
	v_sub_f32_e32 v130, v130, v247
	v_exp_f32_e32 v130, v130
	v_add_f32_e32 v248, v129, v248
	v_mfma_f32_16x16x32_bf16 v[76:79], v[238:241], v[88:91], v[76:79]
	v_sub_f32_e32 v131, v131, v247
	v_exp_f32_e32 v131, v131
	v_add_f32_e32 v248, v130, v248
	v_add_f32_e32 v248, v131, v248
	v_mfma_f32_16x16x32_bf16 v[80:83], v[238:241], v[96:99], v[80:83]
	v_cvt_pk_bf16_f32 v84, v124, v125
	v_cvt_pk_bf16_f32 v85, v126, v127
	v_cvt_pk_bf16_f32 v86, v120, v121
	v_cvt_pk_bf16_f32 v87, v122, v123
	v_cvt_pk_bf16_f32 v88, v112, v113
	v_cvt_pk_bf16_f32 v89, v114, v115
	v_cvt_pk_bf16_f32 v90, v116, v117
	v_cvt_pk_bf16_f32 v91, v118, v119
	v_cvt_pk_bf16_f32 v92, v104, v105
	v_cvt_pk_bf16_f32 v93, v106, v107
	v_cvt_pk_bf16_f32 v94, v108, v109
	v_cvt_pk_bf16_f32 v95, v110, v111
	v_cvt_pk_bf16_f32 v96, v100, v101
	v_cvt_pk_bf16_f32 v97, v102, v103
	v_cvt_pk_bf16_f32 v98, v128, v129
	v_cvt_pk_bf16_f32 v99, v130, v131
	s_cmp_eq_u64 s[36:37], 0
	s_cbranch_scc1 .Lat_nors0
; DI void attn_item(const Params& p, int l, bool isS, int b, int h, int cp, char* smem) {
;     ...
;   auto apply_scale = [&](const float (&alpha)[2], const float (&psum)[2], const bool (&moved)[2]) {
; #pragma unroll
;     for (int mp = 0; mp < 2; ++mp) {
;       if (moved[mp]) {
;         lrun[mp] *= alpha[mp];
; #pragma unroll
;         for (int n = 0; n < 8; ++n) { ot[mp][n][0] *= alpha[mp]; ot[mp][n][1] *= alpha[mp]; ot[mp][n][2] *= alpha[mp]; ot[mp][n][3] *= alpha[mp]; }
;       }
	v_sub_f32_e32 v244, v153, v246
	v_exp_f32_e32 v244, v244
	s_nop 0
	v_mul_f32_e32 v1, v1, v244
	v_pk_mul_f32 v[72:73], v[72:73], v[244:245] op_sel_hi:[1,0]
	v_pk_mul_f32 v[74:75], v[74:75], v[244:245] op_sel_hi:[1,0]
	v_pk_mul_f32 v[60:61], v[60:61], v[244:245] op_sel_hi:[1,0]
	v_pk_mul_f32 v[62:63], v[62:63], v[244:245] op_sel_hi:[1,0]
	v_pk_mul_f32 v[52:53], v[52:53], v[244:245] op_sel_hi:[1,0]
	v_pk_mul_f32 v[54:55], v[54:55], v[244:245] op_sel_hi:[1,0]
	v_pk_mul_f32 v[48:49], v[48:49], v[244:245] op_sel_hi:[1,0]
	v_pk_mul_f32 v[50:51], v[50:51], v[244:245] op_sel_hi:[1,0]
	v_pk_mul_f32 v[40:41], v[40:41], v[244:245] op_sel_hi:[1,0]
	v_pk_mul_f32 v[42:43], v[42:43], v[244:245] op_sel_hi:[1,0]
	v_pk_mul_f32 v[36:37], v[36:37], v[244:245] op_sel_hi:[1,0]
	v_pk_mul_f32 v[38:39], v[38:39], v[244:245] op_sel_hi:[1,0]
	v_pk_mul_f32 v[20:21], v[20:21], v[244:245] op_sel_hi:[1,0]
	v_pk_mul_f32 v[22:23], v[22:23], v[244:245] op_sel_hi:[1,0]
	v_pk_mul_f32 v[76:77], v[76:77], v[244:245] op_sel_hi:[1,0]
	v_pk_mul_f32 v[78:79], v[78:79], v[244:245] op_sel_hi:[1,0]

; DI void attn_item(const Params& p, int l, bool isS, int b, int h, int cp, char* smem) {
;     ...
;   if (wactive) {
;     float l0 = lrun[0], l1 = lrun[1];
;     l0 += __shfl_xor(l0, 16); l0 += __shfl_xor(l0, 32);
;     l1 += __shfl_xor(l1, 16); l1 += __shfl_xor(l1, 32);
;     const float lam = ((const float*)(p.ws + O_LAM))[l];
;     const float lam_init = 0.8f - 0.6f * __expf(-0.3f * (float)l);
;     const float i0 = 1.f / l0, i1 = lam / l1;
;     float ss = 0.f;
; #pragma unroll
;     for (int n = 0; n < 8; ++n)
; #pragma unroll
;       for (int j = 0; j < 4; ++j) { float o = ot[0][n][j] * i0 - ot[1][n][j] * i1; ot[0][n][j] = o; ss += o * o; }
;     ss += __shfl_xor(ss, 16); ss += __shfl_xor(ss, 32);
;     const float rs = rsqrtf(ss * (1.f / 128.f) + EPS) * (1.f - lam_init);
;     const float* g = p.in[11] + (size_t)l * 128;
;     u16* OA = (u16*)(p.ws + O_OA) + (size_t)qrow * 512 + h * 128;
; #pragma unroll
;     for (int n = 0; n < 8; ++n) {
;       const int vd = n * 16 + fq * 4;
;       float4 gg = *(const float4*)(g + vd);
.LBB0_1388:
	v_readlane_b32 s30, v251, 7
	v_readlane_b32 s31, v251, 8
	s_and_saveexec_b64 s[26:27], s[12:13]
	s_cbranch_execz .LBB0_1312
	global_load_dword v4, v173, s[4:5]
	v_xor_b32_e32 v2, 16, v190
	v_cmp_lt_i32_e32 vcc, v2, v191
	s_mov_b32 s9, s21
	v_mov_b32_e32 v133, v173
	v_cndmask_b32_e32 v2, v190, v2, vcc
	v_lshlrev_b32_e32 v85, 2, v2
	ds_bpermute_b32 v2, v85, v1
	s_waitcnt lgkmcnt(0)
	v_add_f32_e32 v1, v1, v2
	v_xor_b32_e32 v2, 32, v190
	v_cmp_lt_i32_e32 vcc, v2, v191
	s_nop 1
	v_cndmask_b32_e32 v2, v190, v2, vcc
	v_lshlrev_b32_e32 v86, 2, v2
	ds_bpermute_b32 v2, v86, v1
	s_waitcnt lgkmcnt(0)
	v_add_f32_e32 v1, v1, v2
	ds_bpermute_b32 v2, v85, v0
	s_waitcnt lgkmcnt(0)
	v_add_f32_e32 v0, v0, v2
	ds_bpermute_b32 v2, v86, v0
	s_waitcnt lgkmcnt(0)
	v_add_f32_e32 v0, v0, v2
	v_div_scale_f32 v2, s[10:11], v1, v1, 1.0
	v_rcp_f32_e32 v5, v2
	s_nop 0
	v_fma_f32 v6, -v2, v5, 1.0
	v_fmac_f32_e32 v5, v6, v5
	v_div_scale_f32 v6, vcc, 1.0, v1, 1.0
	v_mul_f32_e32 v7, v6, v5
	v_fma_f32 v8, -v2, v7, v6
	v_fmac_f32_e32 v7, v8, v5
	v_fma_f32 v2, -v2, v7, v6
	v_div_fmas_f32 v2, v2, v5, v7
	v_div_fixup_f32 v2, v2, v1, 1.0
	s_waitcnt vmcnt(0)
	v_div_scale_f32 v1, s[10:11], v0, v0, v4
	v_rcp_f32_e32 v5, v1
	v_readlane_b32 s10, v252, 59
	v_readlane_b32 s11, v252, 60
	v_fma_f32 v6, -v1, v5, 1.0
	v_fmac_f32_e32 v5, v6, v5
	v_div_scale_f32 v6, vcc, v4, v0, v4
	v_mul_f32_e32 v7, v6, v5
	v_fma_f32 v8, -v1, v7, v6
	v_fmac_f32_e32 v7, v8, v5
	v_fma_f32 v1, -v1, v7, v6
	v_div_fmas_f32 v1, v1, v5, v7
	v_div_fixup_f32 v84, v1, v0, v4
	v_lshl_add_u64 v[4:5], s[10:11], 0, v[134:135]
	v_lshl_add_u64 v[18:19], v[4:5], 0, s[8:9]
	v_pk_mul_f32 v[4:5], v[70:71], v[84:85] op_sel_hi:[1,0]
	v_pk_mul_f32 v[24:25], v[24:25], v[84:85] op_sel_hi:[1,0]
	v_pk_fma_f32 v[10:11], v[74:75], v[2:3], v[4:5] op_sel_hi:[1,0,1] neg_lo:[0,0,1] neg_hi:[0,0,1]
	global_load_dwordx4 v[4:7], v172, s[6:7]
	global_load_dwordx4 v[100:103], v172, s[6:7] offset:64
	global_load_dwordx4 v[104:107], v172, s[6:7] offset:128
	global_load_dwordx4 v[108:111], v172, s[6:7] offset:192
	global_load_dwordx4 v[112:115], v172, s[6:7] offset:256
	global_load_dwordx4 v[116:119], v172, s[6:7] offset:320
	global_load_dwordx4 v[120:123], v172, s[6:7] offset:384
	global_load_dwordx4 v[124:127], v172, s[6:7] offset:448
	v_pk_mul_f32 v[68:69], v[68:69], v[84:85] op_sel_hi:[1,0]
	v_pk_mul_f32 v[26:27], v[26:27], v[84:85] op_sel_hi:[1,0]
	v_pk_fma_f32 v[48:49], v[48:49], v[2:3], v[24:25] op_sel_hi:[1,0,1] neg_lo:[0,0,1] neg_hi:[0,0,1]
	v_pk_mul_f32 v[24:25], v[46:47], v[84:85] op_sel_hi:[1,0]
	v_pk_mul_f32 v[0:1], v[80:81], v[84:85] op_sel_hi:[1,0]
	v_pk_fma_f32 v[68:69], v[72:73], v[2:3], v[68:69] op_sel_hi:[1,0,1] neg_lo:[0,0,1] neg_hi:[0,0,1]
	v_pk_fma_f32 v[50:51], v[50:51], v[2:3], v[26:27] op_sel_hi:[1,0,1] neg_lo:[0,0,1] neg_hi:[0,0,1]
	v_pk_fma_f32 v[26:27], v[42:43], v[2:3], v[24:25] op_sel_hi:[1,0,1] neg_lo:[0,0,1] neg_hi:[0,0,1]
	v_pk_mul_f32 v[24:25], v[44:45], v[84:85] op_sel_hi:[1,0]
	v_pk_fma_f32 v[8:9], v[76:77], v[2:3], v[0:1] op_sel_hi:[1,0,1] neg_lo:[0,0,1] neg_hi:[0,0,1]
	v_pk_mul_f32 v[0:1], v[82:83], v[84:85] op_sel_hi:[1,0]
	v_pk_mul_f32 v[70:71], v[68:69], v[68:69]
	v_pk_mul_f32 v[66:67], v[66:67], v[84:85] op_sel_hi:[1,0]
	v_pk_mul_f32 v[64:65], v[64:65], v[84:85] op_sel_hi:[1,0]
	v_pk_mul_f32 v[58:59], v[58:59], v[84:85] op_sel_hi:[1,0]
	v_pk_mul_f32 v[56:57], v[56:57], v[84:85] op_sel_hi:[1,0]
	v_pk_fma_f32 v[40:41], v[40:41], v[2:3], v[24:25] op_sel_hi:[1,0,1] neg_lo:[0,0,1] neg_hi:[0,0,1]
	v_pk_mul_f32 v[24:25], v[34:35], v[84:85] op_sel_hi:[1,0]
	v_pk_mul_f32 v[32:33], v[32:33], v[84:85] op_sel_hi:[1,0]
	v_pk_mul_f32 v[30:31], v[30:31], v[84:85] op_sel_hi:[1,0]
	v_pk_mul_f32 v[28:29], v[28:29], v[84:85] op_sel_hi:[1,0]
	v_pk_fma_f32 v[0:1], v[78:79], v[2:3], v[0:1] op_sel_hi:[1,0,1] neg_lo:[0,0,1] neg_hi:[0,0,1]
	v_pk_mul_f32 v[16:17], v[10:11], v[10:11]
	v_pk_fma_f32 v[62:63], v[62:63], v[2:3], v[66:67] op_sel_hi:[1,0,1] neg_lo:[0,0,1] neg_hi:[0,0,1]
	v_pk_fma_f32 v[60:61], v[60:61], v[2:3], v[64:65] op_sel_hi:[1,0,1] neg_lo:[0,0,1] neg_hi:[0,0,1]
	v_pk_fma_f32 v[54:55], v[54:55], v[2:3], v[58:59] op_sel_hi:[1,0,1] neg_lo:[0,0,1] neg_hi:[0,0,1]
	v_pk_fma_f32 v[52:53], v[52:53], v[2:3], v[56:57] op_sel_hi:[1,0,1] neg_lo:[0,0,1] neg_hi:[0,0,1]
	v_pk_fma_f32 v[24:25], v[38:39], v[2:3], v[24:25] op_sel_hi:[1,0,1] neg_lo:[0,0,1] neg_hi:[0,0,1]
	v_pk_fma_f32 v[32:33], v[36:37], v[2:3], v[32:33] op_sel_hi:[1,0,1] neg_lo:[0,0,1] neg_hi:[0,0,1]
	v_pk_fma_f32 v[22:23], v[22:23], v[2:3], v[30:31] op_sel_hi:[1,0,1] neg_lo:[0,0,1] neg_hi:[0,0,1]
	v_pk_fma_f32 v[20:21], v[20:21], v[2:3], v[28:29] op_sel_hi:[1,0,1] neg_lo:[0,0,1] neg_hi:[0,0,1]
	v_add_f32_e32 v2, v70, v71
	v_add_f32_e32 v2, v16, v2
	v_pk_mul_f32 v[64:65], v[60:61], v[60:61]
	v_add_f32_e32 v2, v17, v2
	v_add_f32_e32 v2, v64, v2
	v_pk_mul_f32 v[66:67], v[62:63], v[62:63]
	v_add_f32_e32 v2, v65, v2
	v_add_f32_e32 v2, v66, v2
	v_pk_mul_f32 v[56:57], v[52:53], v[52:53]
	v_add_f32_e32 v2, v67, v2
	v_add_f32_e32 v2, v56, v2
	v_pk_mul_f32 v[58:59], v[54:55], v[54:55]
	v_add_f32_e32 v2, v57, v2
	v_add_f32_e32 v2, v58, v2
	v_pk_mul_f32 v[74:75], v[48:49], v[48:49]
	v_add_f32_e32 v2, v59, v2
	v_add_f32_e32 v2, v74, v2
	v_pk_mul_f32 v[72:73], v[50:51], v[50:51]
	v_add_f32_e32 v2, v75, v2
	v_add_f32_e32 v2, v72, v2
	v_pk_mul_f32 v[44:45], v[40:41], v[40:41]
	v_add_f32_e32 v2, v73, v2
	v_add_f32_e32 v2, v44, v2
	v_pk_mul_f32 v[42:43], v[26:27], v[26:27]
	v_add_f32_e32 v2, v45, v2
	v_add_f32_e32 v2, v42, v2
	v_pk_mul_f32 v[36:37], v[32:33], v[32:33]
	v_add_f32_e32 v2, v43, v2
	v_add_f32_e32 v2, v36, v2
	v_pk_mul_f32 v[34:35], v[24:25], v[24:25]
	v_add_f32_e32 v2, v37, v2
	v_add_f32_e32 v2, v34, v2
	v_pk_mul_f32 v[28:29], v[20:21], v[20:21]
	v_add_f32_e32 v2, v35, v2
	v_add_f32_e32 v2, v28, v2
	v_pk_mul_f32 v[30:31], v[22:23], v[22:23]
	v_add_f32_e32 v2, v29, v2
	v_add_f32_e32 v2, v30, v2
	v_pk_mul_f32 v[12:13], v[8:9], v[8:9]
	v_add_f32_e32 v2, v31, v2
	v_add_f32_e32 v2, v12, v2
	v_pk_mul_f32 v[14:15], v[0:1], v[0:1]
	v_add_f32_e32 v2, v13, v2
	v_add_f32_e32 v2, v14, v2
	v_add_f32_e32 v2, v15, v2
	ds_bpermute_b32 v12, v85, v2
	v_lshl_add_u64 v[18:19], v[18:19], 0, v[132:133]
	s_waitcnt lgkmcnt(0)
; DI unsigned pack2(float a, float b) { f32v2_t v = {a, b}; bf16v2_t r = __builtin_convertvector(v, bf16v2_t); return __builtin_bit_cast(unsigned, r); }
; DI void attn_item(const Params& p, int l, bool isS, int b, int h, int cp, char* smem) {
;     ...
;     const float rs = rsqrtf(ss * (1.f / 128.f) + EPS) * (1.f - lam_init);
;     const float* g = p.in[11] + (size_t)l * 128;
;     u16* OA = (u16*)(p.ws + O_OA) + (size_t)qrow * 512 + h * 128;
; #pragma unroll
;     for (int n = 0; n < 8; ++n) {
;       const int vd = n * 16 + fq * 4;
;       float4 gg = *(const float4*)(g + vd);
;       *(uint2*)(OA + vd) = uint2{pack2(ot[0][n][0] * rs * gg.x, ot[0][n][1] * rs * gg.y), pack2(ot[0][n][2] * rs * gg.z, ot[0][n][3] * rs * gg.w)};
;     }
	v_add_f32_e32 v2, v2, v12
	ds_bpermute_b32 v12, v86, v2
	s_waitcnt lgkmcnt(0)
	v_add_f32_e32 v2, v2, v12
	v_fmamk_f32 v2, v2, 0x3c000000, v186
	v_cmp_gt_f32_e32 vcc, s1, v2
	v_mul_f32_e32 v12, 0x4b800000, v2
	s_nop 0
	v_cndmask_b32_e32 v2, v2, v12, vcc
	v_rsq_f32_e32 v2, v2
	s_nop 0
	v_mul_f32_e32 v12, 0x45800000, v2
	v_cndmask_b32_e32 v2, v2, v12, vcc
	v_mul_f32_e32 v2, v144, v2
	v_pk_mul_f32 v[12:13], v[68:69], v[2:3] op_sel_hi:[1,0]
	v_pk_mul_f32 v[10:11], v[10:11], v[2:3] op_sel_hi:[1,0]
	s_waitcnt vmcnt(7)
	v_pk_mul_f32 v[4:5], v[4:5], v[12:13]
	v_pk_mul_f32 v[6:7], v[6:7], v[10:11]
	v_cvt_pk_bf16_f32 v4, v4, v5
	v_cvt_pk_bf16_f32 v5, v6, v7
	global_store_dwordx2 v[18:19], v[4:5], off
	v_pk_mul_f32 v[10:11], v[60:61], v[2:3] op_sel_hi:[1,0]
	v_pk_mul_f32 v[8:9], v[8:9], v[2:3] op_sel_hi:[1,0]
	v_pk_mul_f32 v[0:1], v[0:1], v[2:3] op_sel_hi:[1,0]
	s_waitcnt vmcnt(7)
	v_pk_mul_f32 v[4:5], v[100:101], v[10:11]
	v_pk_mul_f32 v[10:11], v[62:63], v[2:3] op_sel_hi:[1,0]
	v_cvt_pk_bf16_f32 v4, v4, v5
	v_pk_mul_f32 v[6:7], v[102:103], v[10:11]
	v_pk_mul_f32 v[10:11], v[52:53], v[2:3] op_sel_hi:[1,0]
	v_cvt_pk_bf16_f32 v5, v6, v7
	global_store_dwordx2 v[18:19], v[4:5], off offset:32
	s_waitcnt vmcnt(7)
	v_pk_mul_f32 v[4:5], v[104:105], v[10:11]
	v_pk_mul_f32 v[10:11], v[54:55], v[2:3] op_sel_hi:[1,0]
	v_cvt_pk_bf16_f32 v4, v4, v5
	v_pk_mul_f32 v[6:7], v[106:107], v[10:11]
	v_pk_mul_f32 v[10:11], v[48:49], v[2:3] op_sel_hi:[1,0]
	v_cvt_pk_bf16_f32 v5, v6, v7
	global_store_dwordx2 v[18:19], v[4:5], off offset:64
	s_waitcnt vmcnt(7)
	v_pk_mul_f32 v[4:5], v[108:109], v[10:11]
	v_pk_mul_f32 v[10:11], v[50:51], v[2:3] op_sel_hi:[1,0]
	v_cvt_pk_bf16_f32 v4, v4, v5
	v_pk_mul_f32 v[6:7], v[110:111], v[10:11]
	v_pk_mul_f32 v[10:11], v[40:41], v[2:3] op_sel_hi:[1,0]
	v_cvt_pk_bf16_f32 v5, v6, v7
	global_store_dwordx2 v[18:19], v[4:5], off offset:96
	s_waitcnt vmcnt(7)
	v_pk_mul_f32 v[4:5], v[112:113], v[10:11]
	v_pk_mul_f32 v[10:11], v[26:27], v[2:3] op_sel_hi:[1,0]
	v_cvt_pk_bf16_f32 v4, v4, v5
	v_pk_mul_f32 v[6:7], v[114:115], v[10:11]
	v_pk_mul_f32 v[10:11], v[32:33], v[2:3] op_sel_hi:[1,0]
	v_cvt_pk_bf16_f32 v5, v6, v7
	global_store_dwordx2 v[18:19], v[4:5], off offset:128
	s_waitcnt vmcnt(7)
	v_pk_mul_f32 v[4:5], v[116:117], v[10:11]
	v_pk_mul_f32 v[10:11], v[24:25], v[2:3] op_sel_hi:[1,0]
	v_cvt_pk_bf16_f32 v4, v4, v5
	v_pk_mul_f32 v[6:7], v[118:119], v[10:11]
	v_pk_mul_f32 v[10:11], v[20:21], v[2:3] op_sel_hi:[1,0]
	v_cvt_pk_bf16_f32 v5, v6, v7
	global_store_dwordx2 v[18:19], v[4:5], off offset:160
	s_waitcnt vmcnt(7)
	v_pk_mul_f32 v[4:5], v[120:121], v[10:11]
	v_pk_mul_f32 v[10:11], v[22:23], v[2:3] op_sel_hi:[1,0]
	v_cvt_pk_bf16_f32 v4, v4, v5
	v_pk_mul_f32 v[6:7], v[122:123], v[10:11]
	s_nop 0
	v_cvt_pk_bf16_f32 v5, v6, v7
	global_store_dwordx2 v[18:19], v[4:5], off offset:192
	s_waitcnt vmcnt(7)
	v_pk_mul_f32 v[4:5], v[124:125], v[8:9]
	v_pk_mul_f32 v[0:1], v[126:127], v[0:1]
	v_cvt_pk_bf16_f32 v4, v4, v5
	v_cvt_pk_bf16_f32 v5, v0, v1
	global_store_dwordx2 v[18:19], v[4:5], off offset:224
	s_branch .LBB0_1312
